# p2 h1 sample chunks: the 16 state-row loads issued in two batches of eight (two waits instead of sixteen)
# baseline (speedup 1.0000x reference)
; DEVI void h1_item(const Params& P, int l, int ck, int h, char* smem, int tid) {
;     ...
;   f32x4 acc[2][8];
; #pragma unroll
;   for (int mi = 0; mi < 2; ++mi)
; #pragma unroll
;     for (int n = 0; n < 8; ++n) acc[mi][n] = f32x4{0.f, 0.f, 0.f, 0.f};
; #pragma unroll
;   for (int kk = 0; kk < 2; ++kk) {
;     bf16x8 a[2];
; #pragma unroll
;     for (int mi = 0; mi < 2; ++mi) a[mi] = *reinterpret_cast<const bf16x8*>(VT + ((2 * w + mi) * 16 + fr) * 72 + kk * 32 + fq * 8);
; #pragma unroll
;     for (int n = 0; n < 8; ++n) {
;       bf16x8 b = *reinterpret_cast<const bf16x8*>(KT + (n * 16 + fr) * 72 + kk * 32 + fq * 8);
; #pragma unroll
;       for (int mi = 0; mi < 2; ++mi) acc[mi][n] = __builtin_amdgcn_mfma_f32_16x16x32_bf16(a[mi], b, acc[mi][n], 0, 0, 0);
;     }
;   }
;   if (!ci.sample) {
.LBB0_407:
	s_or_b64 exec, exec, s[26:27]
	s_waitcnt lgkmcnt(0)
	s_barrier
	ds_read_b128 v[0:3], v168
	ds_read_b128 v[4:7], v168 offset:2304
	ds_read_b128 v[8:11], v169 offset:18432
	ds_read_b128 v[24:27], v169 offset:23040
	ds_read_b128 v[32:35], v169 offset:25344
	s_waitcnt lgkmcnt(0)
	v_mfma_f32_16x16x32_bf16 v[44:47], v[0:3], v[32:35], 0
	ds_read_b128 v[16:19], v169 offset:20736
	s_mov_b64 s[26:27], -1
	s_and_b64 vcc, exec, s[46:47]
	v_mfma_f32_16x16x32_bf16 v[48:51], v[4:7], v[32:35], 0
	ds_read_b128 v[32:35], v169 offset:27648
	s_waitcnt lgkmcnt(0)
	v_mfma_f32_16x16x32_bf16 v[52:55], v[0:3], v[32:35], 0
	v_mfma_f32_16x16x32_bf16 v[56:59], v[4:7], v[32:35], 0
	ds_read_b128 v[32:35], v169 offset:29952
	s_waitcnt lgkmcnt(0)
	v_mfma_f32_16x16x32_bf16 v[60:63], v[0:3], v[32:35], 0
	v_mfma_f32_16x16x32_bf16 v[170:173], v[4:7], v[32:35], 0
	ds_read_b128 v[32:35], v169 offset:32256
	s_waitcnt lgkmcnt(0)
	v_mfma_f32_16x16x32_bf16 v[174:177], v[0:3], v[32:35], 0
	v_mfma_f32_16x16x32_bf16 v[178:181], v[4:7], v[32:35], 0
	ds_read_b128 v[32:35], v169 offset:34560
	v_mfma_f32_16x16x32_bf16 v[12:15], v[0:3], v[8:11], 0
	v_mfma_f32_16x16x32_bf16 v[20:23], v[0:3], v[16:19], 0
	v_mfma_f32_16x16x32_bf16 v[28:31], v[0:3], v[24:27], 0
	s_waitcnt lgkmcnt(0)
	v_mfma_f32_16x16x32_bf16 v[196:199], v[0:3], v[32:35], 0
	ds_read_b128 v[204:207], v168 offset:64
	ds_read_b128 v[208:211], v168 offset:2368
	ds_read_b128 v[0:3], v169 offset:18496
	v_mfma_f32_16x16x32_bf16 v[8:11], v[4:7], v[8:11], 0
	v_mfma_f32_16x16x32_bf16 v[16:19], v[4:7], v[16:19], 0
	v_mfma_f32_16x16x32_bf16 v[24:27], v[4:7], v[24:27], 0
	v_mfma_f32_16x16x32_bf16 v[200:203], v[4:7], v[32:35], 0
	ds_read_b128 v[4:7], v169 offset:20800
	s_waitcnt lgkmcnt(1)
	v_mfma_f32_16x16x32_bf16 v[32:35], v[204:207], v[0:3], v[12:15]
	v_mfma_f32_16x16x32_bf16 v[0:3], v[208:211], v[0:3], v[8:11]
	s_nop 1
	ds_read_b128 v[12:15], v169 offset:25408
	ds_read_b128 v[8:11], v169 offset:23104
	s_waitcnt lgkmcnt(0)
	v_mfma_f32_16x16x32_bf16 v[40:43], v[204:207], v[8:11], v[28:31]
	s_nop 2
	ds_read_b128 v[28:31], v169 offset:34624
	v_mfma_f32_16x16x32_bf16 v[36:39], v[204:207], v[4:7], v[20:23]
	v_mfma_f32_16x16x32_bf16 v[4:7], v[208:211], v[4:7], v[16:19]
	s_nop 1
	ds_read_b128 v[20:23], v169 offset:30016
	ds_read_b128 v[16:19], v169 offset:27712
	v_mfma_f32_16x16x32_bf16 v[8:11], v[208:211], v[8:11], v[24:27]
	s_nop 2
	ds_read_b128 v[24:27], v169 offset:32320
	v_mfma_f32_16x16x32_bf16 v[44:47], v[204:207], v[12:15], v[44:47]
	v_mfma_f32_16x16x32_bf16 v[12:15], v[208:211], v[12:15], v[48:51]
	s_waitcnt lgkmcnt(1)
	v_mfma_f32_16x16x32_bf16 v[48:51], v[204:207], v[16:19], v[52:55]
	v_mfma_f32_16x16x32_bf16 v[16:19], v[208:211], v[16:19], v[56:59]
	v_mfma_f32_16x16x32_bf16 v[52:55], v[204:207], v[20:23], v[60:63]
	v_mfma_f32_16x16x32_bf16 v[20:23], v[208:211], v[20:23], v[170:173]
	s_waitcnt lgkmcnt(0)
	v_mfma_f32_16x16x32_bf16 v[56:59], v[204:207], v[24:27], v[174:177]
	v_mfma_f32_16x16x32_bf16 v[24:27], v[208:211], v[24:27], v[178:181]
	v_mfma_f32_16x16x32_bf16 v[60:63], v[204:207], v[28:31], v[196:199]
	v_mfma_f32_16x16x32_bf16 v[28:31], v[208:211], v[28:31], v[200:203]
	s_cbranch_vccz .LBB0_409
; DEVI void h1_item(const Params& P, int l, int ck, int h, char* smem, int tid) {
;     ...
;     long sb = ((long)((l * 8 + ci.seqi) * 8 + h)) << 14;
;     const float* S0 = P.in[5] + sb;
;     float* So = P.out + OUT_HGS + sb;
; #pragma unroll
;     for (int mi = 0; mi < 2; ++mi)
; #pragma unroll
;       for (int n = 0; n < 8; ++n) {
;         __builtin_amdgcn_sched_barrier(0);
;         int e0 = (2 * w + mi) * 16 + fq * 4, dd = n * 16 + fr;
;         float4 s0 = *reinterpret_cast<const float4*>(S0 + dd * 128 + e0);
;         float dcl = decl[dd];
;         float4 r;
;         r.x = dcl * s0.x + acc[mi][n][0]; r.y = dcl * s0.y + acc[mi][n][1];
;         r.z = dcl * s0.z + acc[mi][n][2]; r.w = dcl * s0.w + acc[mi][n][3];
;         *reinterpret_cast<float4*>(So + dd * 128 + e0) = r;
;       }
	s_lshl_b32 s24, s50, 3
	s_add_i32 s24, s24, s1
	s_or_b32 s26, s24, s52
	s_ashr_i32 s27, s26, 31
	s_lshl_b64 s[26:27], s[26:27], 16
	v_lshl_add_u64 v[174:175], v[132:133], 0, s[26:27]
	v_lshl_add_u64 v[176:177], v[134:135], 0, s[26:27]
	v_mov_b32_e32 v145, v89
	v_lshl_add_u64 v[178:179], v[174:175], 0, v[144:145]
	v_lshl_add_u64 v[180:181], v[176:177], 0, v[144:145]
	v_mov_b32_e32 v147, v89
	v_lshl_add_u64 v[182:183], v[174:175], 0, v[146:147]
	v_lshl_add_u64 v[196:197], v[176:177], 0, v[146:147]
	v_mov_b32_e32 v149, v89
	v_lshl_add_u64 v[198:199], v[174:175], 0, v[148:149]
	v_lshl_add_u64 v[200:201], v[176:177], 0, v[148:149]
	v_mov_b32_e32 v151, v89
	v_lshl_add_u64 v[202:203], v[174:175], 0, v[150:151]
	v_lshl_add_u64 v[204:205], v[176:177], 0, v[150:151]
	v_mov_b32_e32 v153, v89
	v_lshl_add_u64 v[206:207], v[174:175], 0, v[152:153]
	v_lshl_add_u64 v[208:209], v[176:177], 0, v[152:153]
	v_mov_b32_e32 v155, v89
	v_lshl_add_u64 v[210:211], v[174:175], 0, v[154:155]
	v_lshl_add_u64 v[212:213], v[176:177], 0, v[154:155]
	v_mov_b32_e32 v157, v89
	v_lshl_add_u64 v[214:215], v[174:175], 0, v[156:157]
	v_lshl_add_u64 v[216:217], v[176:177], 0, v[156:157]
	v_mov_b32_e32 v159, v89
	v_lshl_add_u64 v[174:175], v[174:175], 0, v[158:159]
	v_lshl_add_u64 v[176:177], v[176:177], 0, v[158:159]
	global_load_dwordx4 v[220:223], v[178:179], off
	global_load_dwordx4 v[224:227], v[182:183], off
	global_load_dwordx4 v[228:231], v[198:199], off
	global_load_dwordx4 v[232:235], v[202:203], off
	global_load_dwordx4 v[236:239], v[206:207], off
	global_load_dwordx4 v[240:243], v[210:211], off
	global_load_dwordx4 v[244:247], v[214:215], off
	global_load_dwordx4 v[248:251], v[174:175], off
	s_waitcnt vmcnt(0)
	ds_read_b32 v88, v161 offset:55296
	s_waitcnt lgkmcnt(0)
	v_pk_fma_f32 v[220:221], v[220:221], v[88:89], v[32:33] op_sel_hi:[1,0,1]
	v_pk_fma_f32 v[222:223], v[222:223], v[88:89], v[34:35] op_sel_hi:[1,0,1]
	global_store_dwordx4 v[180:181], v[220:223], off
	ds_read_b32 v88, v161 offset:55360
	s_waitcnt lgkmcnt(0)
	v_pk_fma_f32 v[224:225], v[224:225], v[88:89], v[36:37] op_sel_hi:[1,0,1]
	v_pk_fma_f32 v[226:227], v[226:227], v[88:89], v[38:39] op_sel_hi:[1,0,1]
	global_store_dwordx4 v[196:197], v[224:227], off
	ds_read_b32 v88, v161 offset:55424
	s_waitcnt lgkmcnt(0)
	v_pk_fma_f32 v[228:229], v[228:229], v[88:89], v[40:41] op_sel_hi:[1,0,1]
	v_pk_fma_f32 v[230:231], v[230:231], v[88:89], v[42:43] op_sel_hi:[1,0,1]
	global_store_dwordx4 v[200:201], v[228:231], off
	ds_read_b32 v88, v161 offset:55488
	s_waitcnt lgkmcnt(0)
	v_pk_fma_f32 v[232:233], v[232:233], v[88:89], v[44:45] op_sel_hi:[1,0,1]
	v_pk_fma_f32 v[234:235], v[234:235], v[88:89], v[46:47] op_sel_hi:[1,0,1]
	global_store_dwordx4 v[204:205], v[232:235], off
	ds_read_b32 v88, v161 offset:55552
	s_waitcnt lgkmcnt(0)
	v_pk_fma_f32 v[236:237], v[236:237], v[88:89], v[48:49] op_sel_hi:[1,0,1]
	v_pk_fma_f32 v[238:239], v[238:239], v[88:89], v[50:51] op_sel_hi:[1,0,1]
	global_store_dwordx4 v[208:209], v[236:239], off
	ds_read_b32 v88, v161 offset:55616
	s_waitcnt lgkmcnt(0)
	v_pk_fma_f32 v[240:241], v[240:241], v[88:89], v[52:53] op_sel_hi:[1,0,1]
	v_pk_fma_f32 v[242:243], v[242:243], v[88:89], v[54:55] op_sel_hi:[1,0,1]
	global_store_dwordx4 v[212:213], v[240:243], off
	ds_read_b32 v88, v161 offset:55680
	s_waitcnt lgkmcnt(0)
	v_pk_fma_f32 v[244:245], v[244:245], v[88:89], v[56:57] op_sel_hi:[1,0,1]
	v_pk_fma_f32 v[246:247], v[246:247], v[88:89], v[58:59] op_sel_hi:[1,0,1]
	global_store_dwordx4 v[216:217], v[244:247], off
	ds_read_b32 v88, v161 offset:55744
	s_waitcnt lgkmcnt(0)
	v_pk_fma_f32 v[248:249], v[248:249], v[88:89], v[60:61] op_sel_hi:[1,0,1]
	v_pk_fma_f32 v[250:251], v[250:251], v[88:89], v[62:63] op_sel_hi:[1,0,1]
	global_store_dwordx4 v[176:177], v[248:251], off
	global_load_dwordx4 v[220:223], v[178:179], off offset:64
	global_load_dwordx4 v[224:227], v[182:183], off offset:64
	global_load_dwordx4 v[228:231], v[198:199], off offset:64
	global_load_dwordx4 v[232:235], v[202:203], off offset:64
	global_load_dwordx4 v[236:239], v[206:207], off offset:64
	global_load_dwordx4 v[240:243], v[210:211], off offset:64
	global_load_dwordx4 v[244:247], v[214:215], off offset:64
	global_load_dwordx4 v[248:251], v[174:175], off offset:64
	s_waitcnt vmcnt(0)
	ds_read_b32 v88, v161 offset:55296
	s_waitcnt lgkmcnt(0)
	v_pk_fma_f32 v[220:221], v[220:221], v[88:89], v[0:1] op_sel_hi:[1,0,1]
	v_pk_fma_f32 v[222:223], v[222:223], v[88:89], v[2:3] op_sel_hi:[1,0,1]
	global_store_dwordx4 v[180:181], v[220:223], off offset:64
	ds_read_b32 v88, v161 offset:55360
	s_waitcnt lgkmcnt(0)
	v_pk_fma_f32 v[224:225], v[224:225], v[88:89], v[4:5] op_sel_hi:[1,0,1]
	v_pk_fma_f32 v[226:227], v[226:227], v[88:89], v[6:7] op_sel_hi:[1,0,1]
	global_store_dwordx4 v[196:197], v[224:227], off offset:64
	ds_read_b32 v88, v161 offset:55424
	s_waitcnt lgkmcnt(0)
	v_pk_fma_f32 v[228:229], v[228:229], v[88:89], v[8:9] op_sel_hi:[1,0,1]
	v_pk_fma_f32 v[230:231], v[230:231], v[88:89], v[10:11] op_sel_hi:[1,0,1]
	global_store_dwordx4 v[200:201], v[228:231], off offset:64
	ds_read_b32 v88, v161 offset:55488
	s_waitcnt lgkmcnt(0)
	v_pk_fma_f32 v[232:233], v[232:233], v[88:89], v[12:13] op_sel_hi:[1,0,1]
	v_pk_fma_f32 v[234:235], v[234:235], v[88:89], v[14:15] op_sel_hi:[1,0,1]
	global_store_dwordx4 v[204:205], v[232:235], off offset:64
	ds_read_b32 v88, v161 offset:55552
	s_waitcnt lgkmcnt(0)
	v_pk_fma_f32 v[236:237], v[236:237], v[88:89], v[16:17] op_sel_hi:[1,0,1]
	v_pk_fma_f32 v[238:239], v[238:239], v[88:89], v[18:19] op_sel_hi:[1,0,1]
	global_store_dwordx4 v[208:209], v[236:239], off offset:64
	ds_read_b32 v88, v161 offset:55616
	s_waitcnt lgkmcnt(0)
	v_pk_fma_f32 v[240:241], v[240:241], v[88:89], v[20:21] op_sel_hi:[1,0,1]
	v_pk_fma_f32 v[242:243], v[242:243], v[88:89], v[22:23] op_sel_hi:[1,0,1]
	global_store_dwordx4 v[212:213], v[240:243], off offset:64
	ds_read_b32 v88, v161 offset:55680
	s_waitcnt lgkmcnt(0)
	v_pk_fma_f32 v[244:245], v[244:245], v[88:89], v[24:25] op_sel_hi:[1,0,1]
	v_pk_fma_f32 v[246:247], v[246:247], v[88:89], v[26:27] op_sel_hi:[1,0,1]
	global_store_dwordx4 v[216:217], v[244:247], off offset:64
	ds_read_b32 v88, v161 offset:55744
	s_mov_b64 s[26:27], 0
	s_waitcnt lgkmcnt(0)
	v_pk_fma_f32 v[248:249], v[248:249], v[88:89], v[28:29] op_sel_hi:[1,0,1]
	v_pk_fma_f32 v[250:251], v[250:251], v[88:89], v[30:31] op_sel_hi:[1,0,1]
	global_store_dwordx4 v[176:177], v[248:251], off offset:64
